# v47: second exchange's totals become 1/rms per lane-row in the pn==0 workgroup and are stored directly (no LDS redistribution, two barriers and seven 1/sqrt sequences fewer)
# baseline (speedup 1.0000x reference)
.LBB0_719:
	s_waitcnt vmcnt(0) lgkmcnt(0)
	s_barrier
	s_cmp_lg_u32 s18, 0
	s_cbranch_scc1 .LBB0_596
	s_and_saveexec_b64 s[0:1], s[4:5]
	global_load_dword v3, v[4:5], off sc1
	global_load_dword v6, v[4:5], off offset:4 sc1
	global_load_dword v7, v[4:5], off offset:8 sc1
	global_load_dword v8, v[4:5], off offset:12 sc1
	s_add_u32 s6, s16, 0x9800000
	s_addc_u32 s7, s17, 0
	s_lshl_b32 s2, s28, 8
	v_add_lshl_u32 v9, v226, s2, 2
	s_waitcnt vmcnt(3)
	v_add_f32_e32 v3, 0, v3
	s_waitcnt vmcnt(2)
	v_add_f32_e32 v3, v3, v6
	s_waitcnt vmcnt(1)
	v_add_f32_e32 v3, v3, v7
	s_waitcnt vmcnt(0)
	v_add_f32_e32 v3, v3, v8
	v_fmamk_f32 v3, v3, 0x3a800000, v222
	v_mul_f32_e32 v6, 0x4f800000, v3
	v_cmp_gt_f32_e32 vcc, s73, v3
	s_nop 1
	v_cndmask_b32_e32 v3, v3, v6, vcc
	v_sqrt_f32_e32 v6, v3
	s_nop 0
	v_add_u32_e32 v7, -1, v6
	v_fma_f32 v10, -v7, v6, v3
	v_add_u32_e32 v8, 1, v6
	v_cmp_ge_f32_e64 s[10:11], 0, v10
	s_nop 1
	v_cndmask_b32_e64 v7, v6, v7, s[10:11]
	v_fma_f32 v6, -v8, v6, v3
	v_cmp_lt_f32_e64 s[10:11], 0, v6
	s_nop 1
	v_cndmask_b32_e64 v6, v7, v8, s[10:11]
	v_mul_f32_e32 v7, 0x37800000, v6
	v_cndmask_b32_e32 v6, v6, v7, vcc
	v_cmp_class_f32_e32 vcc, v3, v247
	s_nop 1
	v_cndmask_b32_e32 v3, v6, v3, vcc
	v_div_scale_f32 v6, s[2:3], v3, v3, 1.0
	v_rcp_f32_e32 v7, v6
	s_nop 0
	v_fma_f32 v8, -v6, v7, 1.0
	v_fmac_f32_e32 v7, v8, v7
	v_div_scale_f32 v8, vcc, 1.0, v3, 1.0
	v_mul_f32_e32 v10, v8, v7
	v_fma_f32 v11, -v6, v10, v8
	v_fmac_f32_e32 v10, v11, v7
	v_fma_f32 v6, -v6, v10, v8
	v_div_fmas_f32 v6, v6, v7, v10
	v_div_fixup_f32 v3, v6, v3, 1.0
	global_store_dword v9, v3, s[6:7]
	s_branch .LBB0_595
